# grid barrier: invalidate before first poll (non-leader) / right behind wbl2 with vmcnt(1) (leader)
# speedup vs baseline: 1.0002x; 1.0002x over previous
; __device__ __forceinline__ unsigned xb_ld(unsigned* p)              { return __hip_atomic_load(p, __ATOMIC_RELAXED, __HIP_MEMORY_SCOPE_AGENT); }
; __device__ __forceinline__ unsigned xb_add(unsigned* p, unsigned v) { return __hip_atomic_fetch_add(p, v, __ATOMIC_RELAXED, __HIP_MEMORY_SCOPE_AGENT); }
; #define XB_SPIN(cond, bar) do { unsigned _sp = 0; while (cond) { __builtin_amdgcn_s_sleep(1); \
;     if ((++_sp & 255u) == 0u) { if (xb_ld(&(bar)[XB_TMO])) break; if (_sp > XB_SPIN_CAP) { atomicAdd(&(bar)[XB_TMO], 1u); break; } } } } while (0)
; __device__ __forceinline__ void xcd_barrier(const XcdBarrier& b) {
;     ...
;         unsigned nloc = b.st[0], nx = b.st[1];
;         if (nloc == 0u) { xcd_barrier_complete(bar, b.x, nloc, nx); b.st[0] = nloc; b.st[1] = nx; }
;         const unsigned old = xb_add(&bar[XB_XSUB(b.x)], 1u);
;         const unsigned gen = old / nloc;
;         if (old + 1u == (gen + 1u) * nloc) {
;             __builtin_amdgcn_fence(__ATOMIC_RELEASE, "agent");
;             asm volatile("s_waitcnt vmcnt(0)" ::: "memory");
;             const unsigned og = xb_add(&bar[XB_TOP], 1u);
;             const unsigned tg = og / nx;
;             if (og + 1u == (tg + 1u) * nx) xb_add(&bar[XB_TOPGEN], 1u);
;             else XB_SPIN(xb_ld(&bar[XB_TOPGEN]) == tg, bar);
;             __builtin_amdgcn_fence(__ATOMIC_ACQUIRE, "agent");
;             asm volatile("s_waitcnt vmcnt(0)" ::: "memory");
;         } else {
;             XB_SPIN(xb_ld(&bar[XB_TOPGEN]) == gen, bar);
.LBB0_93:
	s_lshl_b32 s3, s2, 8
	v_readlane_b32 s4, v252, 8
	v_readlane_b32 s5, v252, 9
	s_add_u32 s4, s4, s3
	s_addc_u32 s5, s5, 0
	v_mov_b32_e32 v2, 0x1000
	v_mov_b32_e32 v4, 1
	v_sub_u32_e32 v5, 0, v3
	global_atomic_add v4, v2, v4, s[4:5] offset:1024 sc0
	v_cvt_f32_u32_e32 v2, v3
	v_rcp_iflag_f32_e32 v2, v2
	s_nop 0
	v_mul_f32_e32 v2, 0x4f7ffffe, v2
	v_cvt_u32_f32_e32 v2, v2
	v_mul_lo_u32 v5, v5, v2
	v_mul_hi_u32 v5, v2, v5
	v_add_u32_e32 v2, v2, v5
	s_waitcnt vmcnt(0)
	v_mul_hi_u32 v2, v4, v2
	v_mul_lo_u32 v5, v2, v3
	v_sub_u32_e32 v5, v4, v5
	v_add_u32_e32 v6, 1, v2
	v_cmp_ge_u32_e32 vcc, v5, v3
	v_add_u32_e32 v4, 1, v4
	s_nop 0
	v_cndmask_b32_e32 v2, v2, v6, vcc
	v_sub_u32_e32 v6, v5, v3
	v_cndmask_b32_e32 v5, v5, v6, vcc
	v_add_u32_e32 v6, 1, v2
	v_cmp_ge_u32_e32 vcc, v5, v3
	s_nop 1
	v_cndmask_b32_e32 v2, v2, v6, vcc
	v_mul_lo_u32 v5, v3, v2
	v_add_u32_e32 v3, v5, v3
	v_cmp_ne_u32_e32 vcc, v4, v3
	s_and_saveexec_b64 s[4:5], vcc
	s_xor_b64 s[4:5], exec, s[4:5]
	s_cbranch_execz .LBB0_107
	v_readlane_b32 s6, v252, 8
	s_waitcnt lgkmcnt(0)
	v_mov_b32_e32 v1, 0x3000
	v_readlane_b32 s7, v252, 9
	s_add_u32 s8, s6, 0x3500
	s_addc_u32 s9, s7, 0
	s_nop 2
	buffer_inv sc1
	global_load_dword v1, v1, s[6:7] offset:1280 sc1
	s_waitcnt vmcnt(0)
	v_cmp_eq_u32_e32 vcc, v1, v2
	s_and_saveexec_b64 s[6:7], vcc
	s_cbranch_execz .LBB0_106
	s_mov_b32 s3, 1
	s_mov_b64 s[10:11], 0
	v_mov_b32_e32 v1, 0
	s_branch .LBB0_97

; __device__ __forceinline__ unsigned xb_add(unsigned* p, unsigned v) { return __hip_atomic_fetch_add(p, v, __ATOMIC_RELAXED, __HIP_MEMORY_SCOPE_AGENT); }
; __device__ __forceinline__ void xcd_barrier(const XcdBarrier& b) {
;     ...
;         if (old + 1u == (gen + 1u) * nloc) {
;             __builtin_amdgcn_fence(__ATOMIC_RELEASE, "agent");
;             asm volatile("s_waitcnt vmcnt(0)" ::: "memory");
;             const unsigned og = xb_add(&bar[XB_TOP], 1u);
;             const unsigned tg = og / nx;
;             if (og + 1u == (tg + 1u) * nx) xb_add(&bar[XB_TOPGEN], 1u);
.LBB0_107:
	s_andn2_saveexec_b64 s[4:5], s[4:5]
	s_cbranch_execz .LBB0_125
	s_mov_b64 s[4:5], exec
	buffer_wbl2 sc1
	buffer_inv sc1
	s_waitcnt lgkmcnt(0)
	s_waitcnt vmcnt(1)
	v_mbcnt_lo_u32_b32 v2, s4, 0
	v_mbcnt_hi_u32_b32 v2, s5, v2
	v_cmp_eq_u32_e32 vcc, 0, v2
	s_and_saveexec_b64 s[6:7], vcc
	s_cbranch_execz .LBB0_110
	s_bcnt1_i32_b64 s3, s[4:5]
	v_readlane_b32 s4, v252, 8
	v_mov_b32_e32 v3, 0x3000
	v_mov_b32_e32 v4, s3
	v_readlane_b32 s5, v252, 9
	s_nop 4
	global_atomic_add v3, v3, v4, s[4:5] offset:1024 sc0

; __device__ __forceinline__ unsigned xb_ld(unsigned* p)              { return __hip_atomic_load(p, __ATOMIC_RELAXED, __HIP_MEMORY_SCOPE_AGENT); }
; __device__ __forceinline__ unsigned xb_add(unsigned* p, unsigned v) { return __hip_atomic_fetch_add(p, v, __ATOMIC_RELAXED, __HIP_MEMORY_SCOPE_AGENT); }
; #define XB_SPIN(cond, bar) do { unsigned _sp = 0; while (cond) { __builtin_amdgcn_s_sleep(1); \
;     if ((++_sp & 255u) == 0u) { if (xb_ld(&(bar)[XB_TMO])) break; if (_sp > XB_SPIN_CAP) { atomicAdd(&(bar)[XB_TMO], 1u); break; } } } } while (0)
; __device__ __forceinline__ void xcd_barrier(const XcdBarrier& b) {
;     ...
;         unsigned nloc = b.st[0], nx = b.st[1];
;         if (nloc == 0u) { xcd_barrier_complete(bar, b.x, nloc, nx); b.st[0] = nloc; b.st[1] = nx; }
;         const unsigned old = xb_add(&bar[XB_XSUB(b.x)], 1u);
;         const unsigned gen = old / nloc;
;         if (old + 1u == (gen + 1u) * nloc) {
;             __builtin_amdgcn_fence(__ATOMIC_RELEASE, "agent");
;             asm volatile("s_waitcnt vmcnt(0)" ::: "memory");
;             const unsigned og = xb_add(&bar[XB_TOP], 1u);
;             const unsigned tg = og / nx;
;             if (og + 1u == (tg + 1u) * nx) xb_add(&bar[XB_TOPGEN], 1u);
;             else XB_SPIN(xb_ld(&bar[XB_TOPGEN]) == tg, bar);
;             __builtin_amdgcn_fence(__ATOMIC_ACQUIRE, "agent");
;             asm volatile("s_waitcnt vmcnt(0)" ::: "memory");
;         } else {
;             XB_SPIN(xb_ld(&bar[XB_TOPGEN]) == gen, bar);
.LBB0_333:
	v_readlane_b32 s4, v253, 35
	v_readlane_b32 s5, v253, 36
	v_cvt_f32_u32_e32 v1, v2
	v_sub_u32_e32 v4, 0, v2
	v_rcp_iflag_f32_e32 v1, v1
	s_nop 1
	global_atomic_add v3, v177, v238, s[4:5] sc0
	v_mul_f32_e32 v1, 0x4f7ffffe, v1
	v_cvt_u32_f32_e32 v1, v1
	v_mul_lo_u32 v4, v4, v1
	v_mul_hi_u32 v4, v1, v4
	v_add_u32_e32 v1, v1, v4
	s_waitcnt vmcnt(0)
	v_mul_hi_u32 v1, v3, v1
	v_mul_lo_u32 v4, v1, v2
	v_sub_u32_e32 v4, v3, v4
	v_add_u32_e32 v5, 1, v1
	v_cmp_ge_u32_e32 vcc, v4, v2
	v_add_u32_e32 v3, 1, v3
	s_nop 0
	v_cndmask_b32_e32 v1, v1, v5, vcc
	v_sub_u32_e32 v5, v4, v2
	v_cndmask_b32_e32 v4, v4, v5, vcc
	v_add_u32_e32 v5, 1, v1
	v_cmp_ge_u32_e32 vcc, v4, v2
	s_nop 1
	v_cndmask_b32_e32 v1, v1, v5, vcc
	v_mul_lo_u32 v4, v2, v1
	v_add_u32_e32 v2, v4, v2
	v_cmp_ne_u32_e32 vcc, v3, v2
	s_and_saveexec_b64 s[4:5], vcc
	s_xor_b64 s[4:5], exec, s[4:5]
	s_cbranch_execz .LBB0_347
	v_readlane_b32 s8, v253, 37
	v_readlane_b32 s9, v253, 38
	s_waitcnt lgkmcnt(0)
	s_nop 3
	buffer_inv sc1
	global_load_dword v0, v177, s[8:9] sc1
	s_waitcnt vmcnt(0)
	v_cmp_eq_u32_e32 vcc, v0, v1
	s_and_saveexec_b64 s[8:9], vcc
	s_cbranch_execz .LBB0_346
	s_mov_b32 s3, 1
	s_mov_b64 s[16:17], 0
	s_branch .LBB0_337

; __device__ __forceinline__ unsigned xb_add(unsigned* p, unsigned v) { return __hip_atomic_fetch_add(p, v, __ATOMIC_RELAXED, __HIP_MEMORY_SCOPE_AGENT); }
; __device__ __forceinline__ void xcd_barrier(const XcdBarrier& b) {
;     ...
;         if (old + 1u == (gen + 1u) * nloc) {
;             __builtin_amdgcn_fence(__ATOMIC_RELEASE, "agent");
;             asm volatile("s_waitcnt vmcnt(0)" ::: "memory");
;             const unsigned og = xb_add(&bar[XB_TOP], 1u);
;             const unsigned tg = og / nx;
;             if (og + 1u == (tg + 1u) * nx) xb_add(&bar[XB_TOPGEN], 1u);
.LBB0_347:
	s_andn2_saveexec_b64 s[4:5], s[4:5]
	s_cbranch_execz .LBB0_365
	s_mov_b64 s[4:5], exec
	buffer_wbl2 sc1
	buffer_inv sc1
	s_waitcnt lgkmcnt(0)
	s_waitcnt vmcnt(1)
	v_mbcnt_lo_u32_b32 v1, s4, 0
	v_mbcnt_hi_u32_b32 v1, s5, v1
	v_cmp_eq_u32_e32 vcc, 0, v1
	s_and_saveexec_b64 s[8:9], vcc
	s_cbranch_execz .LBB0_350
	s_bcnt1_i32_b64 s3, s[4:5]
	v_readlane_b32 s4, v253, 39
	v_mov_b32_e32 v2, s3
	v_readlane_b32 s5, v253, 40
	s_nop 4
	global_atomic_add v2, v177, v2, s[4:5] sc0

; __device__ __forceinline__ unsigned xb_ld(unsigned* p)              { return __hip_atomic_load(p, __ATOMIC_RELAXED, __HIP_MEMORY_SCOPE_AGENT); }
; __device__ __forceinline__ unsigned xb_add(unsigned* p, unsigned v) { return __hip_atomic_fetch_add(p, v, __ATOMIC_RELAXED, __HIP_MEMORY_SCOPE_AGENT); }
; #define XB_SPIN(cond, bar) do { unsigned _sp = 0; while (cond) { __builtin_amdgcn_s_sleep(1); \
;     if ((++_sp & 255u) == 0u) { if (xb_ld(&(bar)[XB_TMO])) break; if (_sp > XB_SPIN_CAP) { atomicAdd(&(bar)[XB_TMO], 1u); break; } } } } while (0)
; __device__ __forceinline__ void xcd_barrier(const XcdBarrier& b) {
;     ...
;         unsigned nloc = b.st[0], nx = b.st[1];
;         if (nloc == 0u) { xcd_barrier_complete(bar, b.x, nloc, nx); b.st[0] = nloc; b.st[1] = nx; }
;         const unsigned old = xb_add(&bar[XB_XSUB(b.x)], 1u);
;         const unsigned gen = old / nloc;
;         if (old + 1u == (gen + 1u) * nloc) {
;             __builtin_amdgcn_fence(__ATOMIC_RELEASE, "agent");
;             asm volatile("s_waitcnt vmcnt(0)" ::: "memory");
;             const unsigned og = xb_add(&bar[XB_TOP], 1u);
;             const unsigned tg = og / nx;
;             if (og + 1u == (tg + 1u) * nx) xb_add(&bar[XB_TOPGEN], 1u);
;             else XB_SPIN(xb_ld(&bar[XB_TOPGEN]) == tg, bar);
;             __builtin_amdgcn_fence(__ATOMIC_ACQUIRE, "agent");
;             asm volatile("s_waitcnt vmcnt(0)" ::: "memory");
;         } else {
;             XB_SPIN(xb_ld(&bar[XB_TOPGEN]) == gen, bar);
.LBB0_509:
	v_readlane_b32 s4, v253, 35
	v_readlane_b32 s5, v253, 36
	v_cvt_f32_u32_e32 v1, v2
	v_sub_u32_e32 v4, 0, v2
	v_rcp_iflag_f32_e32 v1, v1
	s_nop 1
	global_atomic_add v3, v177, v238, s[4:5] sc0
	v_mul_f32_e32 v1, 0x4f7ffffe, v1
	v_cvt_u32_f32_e32 v1, v1
	v_mul_lo_u32 v4, v4, v1
	v_mul_hi_u32 v4, v1, v4
	v_add_u32_e32 v1, v1, v4
	s_waitcnt vmcnt(0)
	v_mul_hi_u32 v1, v3, v1
	v_mul_lo_u32 v4, v1, v2
	v_sub_u32_e32 v4, v3, v4
	v_add_u32_e32 v5, 1, v1
	v_cmp_ge_u32_e32 vcc, v4, v2
	v_add_u32_e32 v3, 1, v3
	s_nop 0
	v_cndmask_b32_e32 v1, v1, v5, vcc
	v_sub_u32_e32 v5, v4, v2
	v_cndmask_b32_e32 v4, v4, v5, vcc
	v_add_u32_e32 v5, 1, v1
	v_cmp_ge_u32_e32 vcc, v4, v2
	s_nop 1
	v_cndmask_b32_e32 v1, v1, v5, vcc
	v_mul_lo_u32 v4, v2, v1
	v_add_u32_e32 v2, v4, v2
	v_cmp_ne_u32_e32 vcc, v3, v2
	s_and_saveexec_b64 s[4:5], vcc
	s_xor_b64 s[4:5], exec, s[4:5]
	s_cbranch_execz .LBB0_523
	v_readlane_b32 s6, v253, 37
	v_readlane_b32 s7, v253, 38
	s_waitcnt lgkmcnt(0)
	s_nop 3
	buffer_inv sc1
	global_load_dword v0, v177, s[6:7] sc1
	s_waitcnt vmcnt(0)
	v_cmp_eq_u32_e32 vcc, v0, v1
	s_and_saveexec_b64 s[6:7], vcc
	s_cbranch_execz .LBB0_522
	s_mov_b32 s3, 1
	s_mov_b64 s[8:9], 0
	s_branch .LBB0_513

; __device__ __forceinline__ unsigned xb_add(unsigned* p, unsigned v) { return __hip_atomic_fetch_add(p, v, __ATOMIC_RELAXED, __HIP_MEMORY_SCOPE_AGENT); }
; __device__ __forceinline__ void xcd_barrier(const XcdBarrier& b) {
;     ...
;         if (old + 1u == (gen + 1u) * nloc) {
;             __builtin_amdgcn_fence(__ATOMIC_RELEASE, "agent");
;             asm volatile("s_waitcnt vmcnt(0)" ::: "memory");
;             const unsigned og = xb_add(&bar[XB_TOP], 1u);
;             const unsigned tg = og / nx;
;             if (og + 1u == (tg + 1u) * nx) xb_add(&bar[XB_TOPGEN], 1u);
.LBB0_523:
	s_andn2_saveexec_b64 s[4:5], s[4:5]
	s_cbranch_execz .LBB0_541
	s_mov_b64 s[4:5], exec
	buffer_wbl2 sc1
	buffer_inv sc1
	s_waitcnt lgkmcnt(0)
	s_waitcnt vmcnt(1)
	v_mbcnt_lo_u32_b32 v1, s4, 0
	v_mbcnt_hi_u32_b32 v1, s5, v1
	v_cmp_eq_u32_e32 vcc, 0, v1
	s_and_saveexec_b64 s[6:7], vcc
	s_cbranch_execz .LBB0_526
	s_bcnt1_i32_b64 s3, s[4:5]
	v_readlane_b32 s4, v253, 39
	v_mov_b32_e32 v2, s3
	v_readlane_b32 s5, v253, 40
	s_nop 4
	global_atomic_add v2, v177, v2, s[4:5] sc0
